# P0b row loop: next iteration's 16 x-row loads software-pipelined into spare VGPRs during the output stage (copy instead of load at the next top)
# speedup vs baseline: 1.0026x; 1.0026x over previous
.LBB0_136:
	s_or_b64 exec, exec, s[0:1]
	s_cmpk_lt_i32 s94, 0x4000
	s_cselect_b64 s[0:1], -1, 0
	v_writelane_b32 v251, s0, 41
	s_cmpk_gt_i32 s94, 0x3fff
	v_lshlrev_b32_e32 v204, 4, v202
	v_lshlrev_b32_e32 v200, 3, v202
	v_writelane_b32 v251, s1, 42
	s_cbranch_scc1 .LBB0_140
	s_add_i32 s0, s94, 0x1800
	v_mbcnt_hi_u32_b32 v2, -1, v1
	s_ashr_i32 s1, s0, 31
	v_and_b32_e32 v3, 64, v2
	s_lshl_b64 s[4:5], s[0:1], 11
	v_add_u32_e32 v3, 64, v3
	v_xor_b32_e32 v4, 1, v2
	s_add_u32 s30, s34, s4
	v_cmp_lt_i32_e32 vcc, v4, v3
	s_addc_u32 s31, s35, s5
	s_ashr_i32 s95, s94, 31
	v_cndmask_b32_e32 v4, v2, v4, vcc
	s_lshl_b64 s[4:5], s[94:95], 12
	v_lshlrev_b32_e32 v84, 2, v4
	v_xor_b32_e32 v4, 2, v2
	s_add_u32 s36, s52, s4
	v_cmp_lt_i32_e32 vcc, v4, v3
	s_addc_u32 s37, s53, s5
	s_lshl_b64 s[0:1], s[0:1], 12
	v_cndmask_b32_e32 v4, v2, v4, vcc
	s_add_u32 s56, s52, s0
	v_lshlrev_b32_e32 v85, 2, v4
	v_xor_b32_e32 v4, 4, v2
	s_addc_u32 s57, s53, s1
	s_add_i32 s0, s94, 0x1000
	v_cmp_lt_i32_e32 vcc, v4, v3
	s_ashr_i32 s1, s0, 31
	s_lshl_b64 s[4:5], s[0:1], 11
	v_cndmask_b32_e32 v4, v2, v4, vcc
	v_lshlrev_b32_e32 v86, 2, v4
	v_xor_b32_e32 v4, 8, v2
	s_add_u32 s58, s34, s4
	v_cmp_lt_i32_e32 vcc, v4, v3
	v_mov_b32_e32 v205, 0
	s_addc_u32 s59, s35, s5
	s_lshl_b64 s[4:5], s[94:95], 11
	v_cndmask_b32_e32 v4, v2, v4, vcc
	v_lshl_add_u64 v[74:75], s[60:61], 0, v[204:205]
	s_add_u32 s60, s34, s4
	v_lshlrev_b32_e32 v87, 2, v4
	v_xor_b32_e32 v4, 16, v2
	s_addc_u32 s61, s35, s5
	s_lshl_b64 s[0:1], s[0:1], 12
	v_cmp_lt_i32_e32 vcc, v4, v3
	s_add_u32 s62, s52, s0
	s_addc_u32 s63, s53, s1
	v_cndmask_b32_e32 v4, v2, v4, vcc
	s_add_i32 s0, s94, 0x800
	v_lshlrev_b32_e32 v88, 2, v4
	v_xor_b32_e32 v4, 32, v2
	s_ashr_i32 s1, s0, 31
	v_cmp_lt_i32_e32 vcc, v4, v3
	s_lshl_b64 s[4:5], s[0:1], 11
	s_add_u32 s68, s34, s4
	v_cndmask_b32_e32 v2, v2, v4, vcc
	v_lshlrev_b32_e32 v89, 2, v2
	v_lshlrev_b32_e32 v2, 2, v202
	s_addc_u32 s69, s35, s5
	s_lshl_b64 s[0:1], s[0:1], 12
	v_or_b32_e32 v4, 0x100, v2
	v_or_b32_e32 v6, 0x200, v2
	v_or_b32_e32 v8, 0x300, v2
	s_add_u32 s70, s52, s0
	v_mov_b32_e32 v201, v205
	s_addc_u32 s71, s53, s1
	v_mov_b32_e32 v90, 0x358637bd
	s_mov_b32 s3, 0xf800000
	v_mov_b32_e32 v91, 0x260
	v_lshlrev_b32_e32 v92, 2, v2
	s_movk_i32 s26, 0x7fff
	s_mov_b32 s27, 0xffff0000
	s_mov_b32 s33, 0xd200000
	v_lshlrev_b32_e32 v93, 2, v4
	v_lshlrev_b32_e32 v94, 2, v6
	v_lshlrev_b32_e32 v95, 2, v8
	s_mov_b32 s100, 0
	s_mov_b32 s38, s94
.LBB0_138:
	s_cmp_eq_u32 s100, 0
	s_cbranch_scc1 .Lp0b_xload
	s_waitcnt vmcnt(0)
	global_load_dwordx4 v[6:9], v[74:75], off
	v_mov_b64_e32 v[66:67], v[104:105]
	v_mov_b64_e32 v[68:69], v[106:107]
	v_mov_b64_e32 v[58:59], v[112:113]
	v_mov_b64_e32 v[60:61], v[114:115]
	v_mov_b64_e32 v[54:55], v[116:117]
	v_mov_b64_e32 v[56:57], v[118:119]
	v_mov_b64_e32 v[62:63], v[124:125]
	v_mov_b64_e32 v[64:65], v[126:127]
	v_mov_b64_e32 v[50:51], v[128:129]
	v_mov_b64_e32 v[52:53], v[130:131]
	v_mov_b64_e32 v[42:43], v[132:133]
	v_mov_b64_e32 v[44:45], v[134:135]
	v_mov_b64_e32 v[38:39], v[136:137]
	v_mov_b64_e32 v[40:41], v[138:139]
	v_mov_b64_e32 v[46:47], v[140:141]
	v_mov_b64_e32 v[48:49], v[142:143]
	v_mov_b64_e32 v[34:35], v[144:145]
	v_mov_b64_e32 v[36:37], v[146:147]
	v_mov_b64_e32 v[30:31], v[150:151]
	v_mov_b64_e32 v[32:33], v[152:153]
	v_mov_b64_e32 v[26:27], v[214:215]
	v_mov_b64_e32 v[28:29], v[216:217]
	v_mov_b64_e32 v[22:23], v[218:219]
	v_mov_b64_e32 v[24:25], v[220:221]
	v_mov_b64_e32 v[18:19], v[222:223]
	v_mov_b64_e32 v[20:21], v[224:225]
	v_mov_b64_e32 v[14:15], v[232:233]
	v_mov_b64_e32 v[16:17], v[234:235]
	v_mov_b64_e32 v[10:11], v[236:237]
	v_mov_b64_e32 v[12:13], v[238:239]
	v_mov_b64_e32 v[2:3], v[240:241]
	v_mov_b64_e32 v[4:5], v[242:243]
	s_branch .Lp0b_xdone

.Lp0b_xdone:
	s_ashr_i32 s0, s38, 13
	v_lshl_add_u64 v[72:73], s[60:61], 0, v[200:201]
	v_lshl_add_u64 v[76:77], s[68:69], 0, v[200:201]
	s_mul_i32 s8, s0, 0x1800
	v_add_co_u32_e32 v82, vcc, s33, v72
	v_add_co_u32_e64 v80, s[0:1], s33, v76
	s_ashr_i32 s9, s8, 31
	v_addc_co_u32_e32 v83, vcc, 0, v73, vcc
	v_addc_co_u32_e64 v81, vcc, 0, v77, s[0:1]
	s_lshl_b64 s[0:1], s[8:9], 2
	s_add_u32 s78, s28, s0
	s_addc_u32 s79, s29, s1
	v_lshl_add_u64 v[96:97], s[30:31], 0, v[200:201]
	s_add_u32 s80, s78, 0x1000
	v_add_co_u32_e64 v76, s[6:7], s33, v96
	s_addc_u32 s81, s79, 0
	s_nop 0
	v_addc_co_u32_e64 v77, vcc, 0, v97, s[6:7]
	global_load_dwordx4 v[70:73], v92, s[78:79]
	global_load_dwordx4 v[96:99], v92, s[80:81]
	s_add_i32 s0, s38, 0x800
	s_ashr_i32 s0, s0, 13
	s_mulk_i32 s0, 0x1800
	s_ashr_i32 s1, s0, 31
	s_lshl_b64 s[0:1], s[0:1], 2
	s_add_u32 s54, s28, s0
	s_addc_u32 s55, s29, s1
	s_add_u32 s74, s54, 0x1000
	s_addc_u32 s75, s55, 0
	s_add_i32 s0, s38, 0x1000
	s_ashr_i32 s0, s0, 13
	s_mulk_i32 s0, 0x1800
	s_ashr_i32 s1, s0, 31
	s_lshl_b64 s[0:1], s[0:1], 2
	s_add_u32 s66, s28, s0
	s_addc_u32 s67, s29, s1
	s_add_u32 s72, s66, 0x1000
	s_addc_u32 s73, s67, 0
	s_add_i32 s0, s38, 0x1800
	v_lshl_add_u64 v[78:79], s[58:59], 0, v[200:201]
	s_ashr_i32 s0, s0, 13
	v_add_co_u32_e64 v78, s[4:5], s33, v78
	s_mulk_i32 s0, 0x1800
	s_nop 0
	v_addc_co_u32_e64 v79, vcc, 0, v79, s[4:5]
	s_ashr_i32 s1, s0, 31
	s_lshl_b64 s[0:1], s[0:1], 2
	s_add_u32 s52, s28, s0
	s_addc_u32 s53, s29, s1
	s_add_u32 s64, s52, 0x1000
	s_addc_u32 s65, s53, 0
	s_add_u32 s30, s30, 0x1000000
	s_addc_u32 s31, s31, 0
	s_add_u32 s36, s36, 0x2000000
	s_addc_u32 s37, s37, 0
	s_add_u32 s56, s56, 0x2000000
	s_addc_u32 s57, s57, 0
	s_add_u32 s58, s58, 0x1000000
	s_waitcnt vmcnt(17)
	v_pk_mul_f32 v[100:101], v[68:69], v[68:69]
	v_pk_mul_f32 v[102:103], v[66:67], v[66:67]
	s_waitcnt vmcnt(16)
	v_pk_mul_f32 v[104:105], v[60:61], v[60:61]
	v_pk_mul_f32 v[106:107], v[58:59], v[58:59]
	s_waitcnt vmcnt(13)
	v_pk_mul_f32 v[112:113], v[52:53], v[52:53]
	v_pk_mul_f32 v[114:115], v[50:51], v[50:51]
	s_waitcnt vmcnt(12)
	v_pk_mul_f32 v[116:117], v[44:45], v[44:45]
	v_pk_mul_f32 v[118:119], v[42:43], v[42:43]
	v_mul_f32_e32 v109, v56, v56
	v_mul_f32_e32 v108, v63, v63
	v_mul_f32_e32 v110, v65, v65
	s_waitcnt vmcnt(10)
	v_mul_f32_e32 v120, v47, v47
	v_mul_f32_e32 v122, v49, v49
	s_waitcnt vmcnt(9)
	v_pk_mul_f32 v[124:125], v[36:37], v[36:37]
	v_pk_mul_f32 v[126:127], v[34:35], v[34:35]
	s_waitcnt vmcnt(8)
	v_pk_mul_f32 v[128:129], v[32:33], v[32:33]
	v_pk_mul_f32 v[130:131], v[30:31], v[30:31]
	v_pk_mov_b32 v[140:141], v[102:103], v[100:101] op_sel:[1,0]
	v_mov_b32_e32 v103, v101
	v_pk_mov_b32 v[100:101], v[106:107], v[104:105] op_sel:[1,0]
	v_mov_b32_e32 v107, v105
	v_pk_mov_b32 v[104:105], v[114:115], v[112:113] op_sel:[1,0]
	v_mov_b32_e32 v115, v113
	v_pk_mov_b32 v[112:113], v[118:119], v[116:117] op_sel:[1,0]
	v_mov_b32_e32 v119, v117
	v_mul_f32_e32 v144, v57, v57
	v_mul_f32_e32 v147, v40, v40
	v_mul_f32_e32 v149, v41, v41
	s_waitcnt vmcnt(5)
	v_pk_mul_f32 v[132:133], v[20:21], v[20:21]
	v_pk_mul_f32 v[134:135], v[18:19], v[18:19]
	s_waitcnt vmcnt(4)
	v_pk_mul_f32 v[136:137], v[16:17], v[16:17]
	v_pk_mul_f32 v[138:139], v[14:15], v[14:15]
	v_pk_mov_b32 v[116:117], v[126:127], v[124:125] op_sel:[1,0]
	v_mov_b32_e32 v127, v125
	v_pk_mov_b32 v[124:125], v[130:131], v[128:129] op_sel:[1,0]
	v_mov_b32_e32 v131, v129
	v_pk_add_f32 v[102:103], v[140:141], v[102:103]
	v_pk_add_f32 v[100:101], v[100:101], v[106:107]
	v_pk_fma_f32 v[106:107], v[62:63], v[62:63], v[108:109] op_sel_hi:[1,1,0]
	v_pk_add_f32 v[112:113], v[112:113], v[118:119]
	v_pk_fma_f32 v[110:111], v[64:65], v[64:65], v[110:111] op_sel_hi:[1,1,0]
	v_pk_fma_f32 v[118:119], v[46:47], v[46:47], v[120:121] op_sel_hi:[1,1,0]
	v_pk_fma_f32 v[120:121], v[48:49], v[48:49], v[122:123] op_sel_hi:[1,1,0]
	v_mul_f32_e32 v142, v54, v54
	v_mul_f32_e32 v143, v55, v55
	v_pk_mov_b32 v[128:129], v[134:135], v[132:133] op_sel:[1,0]
	v_mov_b32_e32 v135, v133
	v_pk_mov_b32 v[132:133], v[138:139], v[136:137] op_sel:[1,0]
	v_mul_f32_e32 v136, v27, v27
	v_mul_f32_e32 v140, v29, v29
	s_waitcnt vmcnt(2)
	global_load_dwordx4 v[158:161], v[74:75], off
	global_load_dwordx4 v[174:177], v92, s[80:81]
	global_load_dwordx4 v[190:193], v92, s[78:79]
	global_load_dwordx4 v[162:165], v[74:75], off offset:1024
	global_load_dwordx4 v[178:181], v93, s[80:81]
	global_load_dwordx4 v[194:197], v92, s[78:79] offset:1024
	global_load_dwordx4 v[166:169], v[74:75], off offset:2048
	global_load_dwordx4 v[182:185], v94, s[80:81]
	global_load_dwordx4 v[206:209], v92, s[78:79] offset:2048
	global_load_dwordx4 v[170:173], v[74:75], off offset:3072
	global_load_dwordx4 v[186:189], v95, s[80:81]
	global_load_dwordx4 v[210:213], v92, s[78:79] offset:3072
	v_mul_f32_e32 v141, v2, v2
	v_mov_b32_e32 v107, v109
	v_pk_add_f32 v[104:105], v[104:105], v[114:115]
	v_mov_b32_e32 v111, v144
	v_mov_b32_e32 v119, v147
	v_mov_b32_e32 v121, v149
	v_pk_add_f32 v[116:117], v[116:117], v[126:127]
	v_pk_add_f32 v[124:125], v[124:125], v[130:131]
	v_pk_add_f32 v[102:103], v[102:103], v[102:103] op_sel:[0,1] op_sel_hi:[1,0]
	v_pk_add_f32 v[100:101], v[100:101], v[100:101] op_sel:[0,1] op_sel_hi:[1,0]
	v_mul_f32_e32 v145, v38, v38
	v_mul_f32_e32 v146, v39, v39
	v_mul_f32_e32 v150, v22, v22
	v_mul_f32_e32 v151, v23, v23
	v_mul_f32_e32 v152, v24, v24
	v_mul_f32_e32 v153, v25, v25
	v_mov_b32_e32 v139, v137
	v_pk_fma_f32 v[122:123], v[26:27], v[26:27], v[136:137] op_sel_hi:[1,1,0]
	v_pk_fma_f32 v[136:137], v[28:29], v[28:29], v[140:141] op_sel_hi:[1,1,0]
	v_pk_add_f32 v[106:107], v[106:107], v[110:111]
	v_pk_add_f32 v[104:105], v[104:105], v[104:105] op_sel:[0,1] op_sel_hi:[1,0]
	v_pk_add_f32 v[110:111], v[112:113], v[112:113] op_sel:[0,1] op_sel_hi:[1,0]
	v_pk_add_f32 v[112:113], v[118:119], v[120:121]
	v_pk_add_f32 v[116:117], v[116:117], v[116:117] op_sel:[0,1] op_sel_hi:[1,0]
	v_pk_add_f32 v[118:119], v[124:125], v[124:125] op_sel:[0,1] op_sel_hi:[1,0]
	v_mov_b32_e32 v103, v142
	v_mov_b32_e32 v101, v143
	v_mov_b32_e32 v123, v152
	v_mov_b32_e32 v137, v153
	v_mov_b32_e32 v105, v145
	v_mov_b32_e32 v111, v146
	v_mov_b32_e32 v117, v150
	v_mov_b32_e32 v119, v151
	v_pk_add_f32 v[100:101], v[102:103], v[100:101]
	v_mul_f32_e32 v108, v11, v11
	v_mul_f32_e32 v114, v13, v13
	v_pk_add_f32 v[126:127], v[128:129], v[134:135]
	v_pk_add_f32 v[128:129], v[132:133], v[138:139]
	v_pk_add_f32 v[120:121], v[122:123], v[136:137]
	v_pk_add_f32 v[102:103], v[104:105], v[110:111]
	v_pk_add_f32 v[104:105], v[116:117], v[118:119]
	v_pk_add_f32 v[100:101], v[100:101], v[106:107]
	v_mul_f32_e32 v154, v3, v3
	v_mul_f32_e32 v155, v4, v4
	v_mul_f32_e32 v156, v5, v5
	v_pk_fma_f32 v[108:109], v[10:11], v[10:11], v[108:109] op_sel_hi:[1,1,0]
	v_pk_fma_f32 v[114:115], v[12:13], v[12:13], v[114:115] op_sel_hi:[1,1,0]
	v_pk_add_f32 v[122:123], v[126:127], v[126:127] op_sel:[0,1] op_sel_hi:[1,0]
	v_pk_add_f32 v[124:125], v[128:129], v[128:129] op_sel:[0,1] op_sel_hi:[1,0]
	v_pk_add_f32 v[102:103], v[102:103], v[112:113]
	v_pk_add_f32 v[104:105], v[104:105], v[120:121]
	v_add_f32_e32 v100, v100, v101
	v_mov_b32_e32 v109, v155
	v_mov_b32_e32 v115, v156
	v_mov_b32_e32 v123, v141
	v_mov_b32_e32 v125, v154
	v_add_f32_e32 v101, v102, v103
	v_add_f32_e32 v102, v104, v105
	ds_bpermute_b32 v104, v84, v100
	v_pk_add_f32 v[108:109], v[108:109], v[114:115]
	v_pk_add_f32 v[110:111], v[122:123], v[124:125]
	ds_bpermute_b32 v105, v84, v101
	v_pk_add_f32 v[106:107], v[110:111], v[108:109]
	s_waitcnt lgkmcnt(1)
	v_add_f32_e32 v100, v100, v104
	v_add_f32_e32 v103, v106, v107
	ds_bpermute_b32 v106, v84, v102
	ds_bpermute_b32 v104, v85, v100
	s_waitcnt lgkmcnt(2)
	v_add_f32_e32 v101, v101, v105
	ds_bpermute_b32 v105, v85, v101
	ds_bpermute_b32 v107, v84, v103
	s_waitcnt lgkmcnt(3)
	v_add_f32_e32 v102, v102, v106
	ds_bpermute_b32 v106, v85, v102
	s_waitcnt lgkmcnt(3)
	v_add_f32_e32 v100, v100, v104
	ds_bpermute_b32 v104, v86, v100
	s_waitcnt lgkmcnt(3)
	v_add_f32_e32 v101, v101, v105
	ds_bpermute_b32 v105, v86, v101
	s_waitcnt lgkmcnt(2)
	v_add_f32_e32 v102, v102, v106
	ds_bpermute_b32 v106, v86, v102
	s_waitcnt lgkmcnt(2)
	v_add_f32_e32 v100, v100, v104
	ds_bpermute_b32 v104, v87, v100
	s_waitcnt lgkmcnt(2)
	v_add_f32_e32 v101, v101, v105
	ds_bpermute_b32 v105, v87, v101
	s_waitcnt lgkmcnt(2)
	v_add_f32_e32 v102, v102, v106
	ds_bpermute_b32 v106, v87, v102
	s_waitcnt lgkmcnt(2)
	v_add_f32_e32 v100, v100, v104
	ds_bpermute_b32 v104, v88, v100
	s_waitcnt lgkmcnt(2)
	v_add_f32_e32 v101, v101, v105
	ds_bpermute_b32 v105, v88, v101
	s_waitcnt lgkmcnt(2)
	v_add_f32_e32 v102, v102, v106
	ds_bpermute_b32 v106, v88, v102
	s_waitcnt lgkmcnt(2)
	v_add_f32_e32 v100, v100, v104
	ds_bpermute_b32 v104, v89, v100
	v_add_f32_e32 v103, v103, v107
	s_waitcnt lgkmcnt(2)
	v_add_f32_e32 v101, v101, v105
	ds_bpermute_b32 v107, v85, v103
	s_waitcnt lgkmcnt(2)
	v_add_f32_e32 v102, v102, v106
	ds_bpermute_b32 v105, v89, v101
	ds_bpermute_b32 v106, v89, v102
	s_waitcnt lgkmcnt(3)
	v_add_f32_e32 v100, v100, v104
	v_fmamk_f32 v100, v100, 0x3a800000, v90
	s_waitcnt lgkmcnt(2)
	v_add_f32_e32 v103, v103, v107
	s_waitcnt lgkmcnt(1)
	v_add_f32_e32 v101, v101, v105
	v_cmp_gt_f32_e32 vcc, s3, v100
	v_mul_f32_e32 v104, 0x4f800000, v100
	ds_bpermute_b32 v107, v86, v103
	s_waitcnt lgkmcnt(1)
	v_add_f32_e32 v102, v102, v106
	v_fmamk_f32 v101, v101, 0x3a800000, v90
	v_cndmask_b32_e32 v100, v100, v104, vcc
	v_fmamk_f32 v102, v102, 0x3a800000, v90
	v_cmp_gt_f32_e64 s[0:1], s3, v101
	v_mul_f32_e32 v105, 0x4f800000, v101
	v_sqrt_f32_e32 v104, v100
	v_cmp_gt_f32_e64 s[4:5], s3, v102
	v_mul_f32_e32 v106, 0x4f800000, v102
	v_cndmask_b32_e64 v101, v101, v105, s[0:1]
	v_cndmask_b32_e64 v102, v102, v106, s[4:5]
	v_sqrt_f32_e32 v105, v101
	v_sqrt_f32_e32 v106, v102
	s_waitcnt lgkmcnt(0)
	v_add_f32_e32 v103, v103, v107
	v_add_u32_e32 v107, -1, v104
	v_add_u32_e32 v108, 1, v104
	v_fma_f32 v113, -v107, v104, v100
	v_add_u32_e32 v109, -1, v105
	v_fma_f32 v114, -v108, v104, v100
	v_cmp_ge_f32_e64 s[12:13], 0, v113
	v_add_u32_e32 v110, 1, v105
	v_add_u32_e32 v111, -1, v106
	v_fma_f32 v115, -v109, v105, v101
	v_cmp_lt_f32_e64 s[16:17], 0, v114
	v_cndmask_b32_e64 v104, v104, v107, s[12:13]
	v_add_u32_e32 v112, 1, v106
	v_fma_f32 v116, -v110, v105, v101
	v_fma_f32 v117, -v111, v106, v102
	v_cmp_ge_f32_e64 s[18:19], 0, v115
	v_cndmask_b32_e64 v104, v104, v108, s[16:17]
	v_fma_f32 v118, -v112, v106, v102
	v_cmp_lt_f32_e64 s[20:21], 0, v116
	v_cmp_ge_f32_e64 s[22:23], 0, v117
	v_cndmask_b32_e64 v105, v105, v109, s[18:19]
	v_mul_f32_e32 v107, 0x37800000, v104
	v_cmp_class_f32_e64 s[6:7], v100, v91
	v_cmp_lt_f32_e64 s[24:25], 0, v118
	v_cndmask_b32_e64 v106, v106, v111, s[22:23]
	v_cndmask_b32_e64 v105, v105, v110, s[20:21]
	v_cndmask_b32_e32 v104, v104, v107, vcc
	v_cndmask_b32_e64 v106, v106, v112, s[24:25]
	v_mul_f32_e32 v108, 0x37800000, v105
	v_cndmask_b32_e64 v100, v104, v100, s[6:7]
	v_cmp_class_f32_e64 s[8:9], v101, v91
	v_mul_f32_e32 v109, 0x37800000, v106
	v_cndmask_b32_e64 v105, v105, v108, s[0:1]
	v_div_scale_f32 v104, s[0:1], v100, v100, 1.0
	v_cmp_class_f32_e64 s[10:11], v102, v91
	v_cndmask_b32_e64 v106, v106, v109, s[4:5]
	v_cndmask_b32_e64 v101, v105, v101, s[8:9]
	v_rcp_f32_e32 v110, v104
	v_cndmask_b32_e64 v102, v106, v102, s[10:11]
	v_div_scale_f32 v106, s[0:1], v101, v101, 1.0
	v_div_scale_f32 v108, s[4:5], v102, v102, 1.0
	v_rcp_f32_e32 v111, v106
	v_rcp_f32_e32 v112, v108
	v_fma_f32 v113, -v104, v110, 1.0
	v_div_scale_f32 v105, vcc, 1.0, v100, 1.0
	v_fmac_f32_e32 v110, v113, v110
	v_fma_f32 v114, -v106, v111, 1.0
	v_mul_f32_e32 v113, v105, v110
	v_div_scale_f32 v107, s[0:1], 1.0, v101, 1.0
	v_fma_f32 v115, -v108, v112, 1.0
	v_fmac_f32_e32 v111, v114, v111
	v_fma_f32 v116, -v104, v113, v105
	v_div_scale_f32 v109, s[4:5], 1.0, v102, 1.0
	v_fmac_f32_e32 v112, v115, v112
	v_mul_f32_e32 v114, v107, v111
	v_fmac_f32_e32 v113, v116, v110
	v_mul_f32_e32 v115, v109, v112
	v_fma_f32 v117, -v106, v114, v107
	v_fma_f32 v104, -v104, v113, v105
	v_fma_f32 v118, -v108, v115, v109
	v_fmac_f32_e32 v114, v117, v111
	v_div_fmas_f32 v104, v104, v110, v113
	v_fmac_f32_e32 v115, v118, v112
	v_fma_f32 v105, -v106, v114, v107
	v_div_fixup_f32 v100, v104, v100, 1.0
	s_mov_b64 vcc, s[0:1]
	v_fma_f32 v106, -v108, v115, v109
	v_div_fmas_f32 v104, v105, v111, v114
	v_pk_mul_f32 v[68:69], v[68:69], v[100:101] op_sel_hi:[1,0]
	v_pk_mul_f32 v[66:67], v[66:67], v[100:101] op_sel_hi:[1,0]
	s_mov_b64 vcc, s[4:5]
	s_waitcnt vmcnt(0)
	v_pk_add_f32 v[98:99], v[98:99], 1.0 op_sel_hi:[1,0]
	v_pk_add_f32 v[96:97], v[96:97], 1.0 op_sel_hi:[1,0]
	v_pk_mul_f32 v[60:61], v[60:61], v[100:101] op_sel_hi:[1,0]
	v_pk_mul_f32 v[58:59], v[58:59], v[100:101] op_sel_hi:[1,0]
	v_pk_mul_f32 v[64:65], v[64:65], v[100:101] op_sel_hi:[1,0]
	v_pk_mul_f32 v[62:63], v[62:63], v[100:101] op_sel_hi:[1,0]
	v_pk_mul_f32 v[56:57], v[56:57], v[100:101] op_sel_hi:[1,0]
	v_pk_mul_f32 v[54:55], v[54:55], v[100:101] op_sel_hi:[1,0]
	v_div_fixup_f32 v100, v104, v101, 1.0
	v_div_fmas_f32 v104, v106, v112, v115
	v_pk_mul_f32 v[66:67], v[6:7], v[66:67]
	v_pk_mul_f32 v[8:9], v[8:9], v[68:69]
	v_pk_mul_f32 v[52:53], v[52:53], v[100:101] op_sel_hi:[1,0]
	v_pk_mul_f32 v[50:51], v[50:51], v[100:101] op_sel_hi:[1,0]
	v_pk_mul_f32 v[44:45], v[44:45], v[100:101] op_sel_hi:[1,0]
	v_pk_mul_f32 v[42:43], v[42:43], v[100:101] op_sel_hi:[1,0]
	v_pk_mul_f32 v[48:49], v[48:49], v[100:101] op_sel_hi:[1,0]
	v_pk_mul_f32 v[46:47], v[46:47], v[100:101] op_sel_hi:[1,0]
	v_pk_mul_f32 v[68:69], v[40:41], v[100:101] op_sel_hi:[1,0]
	v_pk_mul_f32 v[100:101], v[38:39], v[100:101] op_sel_hi:[1,0]
	v_div_fixup_f32 v6, v104, v102, 1.0
	v_pk_fma_f32 v[8:9], v[98:99], v[8:9], v[72:73]
	v_pk_fma_f32 v[38:39], v[96:97], v[66:67], v[70:71]
	v_pk_mul_f32 v[66:67], v[36:37], v[6:7] op_sel_hi:[1,0]
	v_pk_mul_f32 v[70:71], v[34:35], v[6:7] op_sel_hi:[1,0]
	v_pk_mul_f32 v[72:73], v[32:33], v[6:7] op_sel_hi:[1,0]
	v_pk_mul_f32 v[96:97], v[30:31], v[6:7] op_sel_hi:[1,0]
	v_cvt_pk_bf16_f32 v9, v8, v9
	v_cvt_pk_bf16_f32 v8, v38, v39
	global_store_dwordx2 v[82:83], v[8:9], off
	s_addc_u32 s59, s59, 0
	s_add_u32 s60, s60, 0x1000000
	s_addc_u32 s61, s61, 0
	s_add_u32 s62, s62, 0x2000000
	s_addc_u32 s63, s63, 0
	s_add_u32 s68, s68, 0x1000000
	s_addc_u32 s69, s69, 0
	s_add_u32 s70, s70, 0x2000000
	s_addc_u32 s71, s71, 0
	s_cmpk_lt_i32 s38, 0x2000
	s_cbranch_scc0 .Lp0b_nopf
	v_lshl_add_u64 v[244:245], s[36:37], 0, v[204:205]
	global_load_dwordx4 v[104:107], v[244:245], off
	global_load_dwordx4 v[112:115], v[244:245], off offset:1024
	global_load_dwordx4 v[116:119], v[244:245], off offset:3072
	global_load_dwordx4 v[124:127], v[244:245], off offset:2048
	v_lshl_add_u64 v[244:245], s[70:71], 0, v[204:205]
	global_load_dwordx4 v[128:131], v[244:245], off
	global_load_dwordx4 v[132:135], v[244:245], off offset:1024
	global_load_dwordx4 v[136:139], v[244:245], off offset:3072
	global_load_dwordx4 v[140:143], v[244:245], off offset:2048
	v_lshl_add_u64 v[244:245], s[62:63], 0, v[204:205]
	global_load_dwordx4 v[144:147], v[244:245], off
	global_load_dwordx4 v[150:153], v[244:245], off offset:1024
	global_load_dwordx4 v[214:217], v[244:245], off offset:2048
	global_load_dwordx4 v[218:221], v[244:245], off offset:3072
	v_lshl_add_u64 v[244:245], s[56:57], 0, v[204:205]
	global_load_dwordx4 v[222:225], v[244:245], off
	global_load_dwordx4 v[232:235], v[244:245], off offset:1024
	global_load_dwordx4 v[236:239], v[244:245], off offset:2048
	global_load_dwordx4 v[240:243], v[244:245], off offset:3072
	s_mov_b32 s100, 1
.Lp0b_nopf:
	v_pk_mul_f32 v[8:9], v[162:163], v[58:59]
	v_pk_mul_f32 v[30:31], v[164:165], v[60:61]
	v_pk_add_f32 v[32:33], v[180:181], 1.0 op_sel_hi:[1,0]
	v_pk_add_f32 v[34:35], v[178:179], 1.0 op_sel_hi:[1,0]
	v_pk_fma_f32 v[30:31], v[32:33], v[30:31], v[196:197]
	v_pk_fma_f32 v[8:9], v[34:35], v[8:9], v[194:195]
	v_cvt_pk_bf16_f32 v8, v8, v9
	v_cvt_pk_bf16_f32 v9, v30, v31
	global_store_dwordx2 v[82:83], v[8:9], off offset:512
	v_pk_mul_f32 v[8:9], v[166:167], v[62:63]
	v_pk_mul_f32 v[30:31], v[168:169], v[64:65]
	v_pk_add_f32 v[32:33], v[184:185], 1.0 op_sel_hi:[1,0]
	v_pk_add_f32 v[34:35], v[182:183], 1.0 op_sel_hi:[1,0]
	v_pk_fma_f32 v[30:31], v[30:31], v[32:33], v[208:209]
	v_pk_fma_f32 v[8:9], v[8:9], v[34:35], v[206:207]
	v_cvt_pk_bf16_f32 v8, v8, v9
	v_cvt_pk_bf16_f32 v9, v30, v31
	global_store_dwordx2 v[82:83], v[8:9], off offset:1024
	v_pk_mul_f32 v[8:9], v[54:55], v[170:171]
	v_pk_mul_f32 v[30:31], v[56:57], v[172:173]
	v_pk_add_f32 v[32:33], v[188:189], 1.0 op_sel_hi:[1,0]
	v_pk_add_f32 v[34:35], v[186:187], 1.0 op_sel_hi:[1,0]
	v_pk_fma_f32 v[30:31], v[30:31], v[32:33], v[212:213]
	v_pk_fma_f32 v[8:9], v[8:9], v[34:35], v[210:211]
	v_cvt_pk_bf16_f32 v8, v8, v9
	v_cvt_pk_bf16_f32 v9, v30, v31
	global_store_dwordx2 v[82:83], v[8:9], off offset:1536
	v_pk_mul_f32 v[8:9], v[158:159], v[50:51]
	v_pk_mul_f32 v[30:31], v[160:161], v[52:53]
	v_pk_add_f32 v[32:33], v[176:177], 1.0 op_sel_hi:[1,0]
	v_pk_add_f32 v[34:35], v[174:175], 1.0 op_sel_hi:[1,0]
	v_pk_fma_f32 v[30:31], v[32:33], v[30:31], v[192:193]
	v_pk_fma_f32 v[8:9], v[34:35], v[8:9], v[190:191]
	v_cvt_pk_bf16_f32 v8, v8, v9
	v_cvt_pk_bf16_f32 v9, v30, v31
	global_store_dwordx2 v[80:81], v[8:9], off
	v_pk_mul_f32 v[8:9], v[162:163], v[42:43]
	v_pk_mul_f32 v[30:31], v[164:165], v[44:45]
	v_pk_add_f32 v[32:33], v[180:181], 1.0 op_sel_hi:[1,0]
	v_pk_add_f32 v[34:35], v[178:179], 1.0 op_sel_hi:[1,0]
	v_pk_fma_f32 v[30:31], v[32:33], v[30:31], v[196:197]
	v_pk_fma_f32 v[8:9], v[34:35], v[8:9], v[194:195]
	v_cvt_pk_bf16_f32 v8, v8, v9
	v_cvt_pk_bf16_f32 v9, v30, v31
	global_store_dwordx2 v[80:81], v[8:9], off offset:512
	v_pk_mul_f32 v[8:9], v[166:167], v[46:47]
	v_pk_mul_f32 v[30:31], v[168:169], v[48:49]
	v_pk_add_f32 v[32:33], v[184:185], 1.0 op_sel_hi:[1,0]
	v_pk_add_f32 v[34:35], v[182:183], 1.0 op_sel_hi:[1,0]
	v_pk_fma_f32 v[30:31], v[30:31], v[32:33], v[208:209]
	v_pk_fma_f32 v[8:9], v[8:9], v[34:35], v[206:207]
	v_cvt_pk_bf16_f32 v8, v8, v9
	v_cvt_pk_bf16_f32 v9, v30, v31
	global_store_dwordx2 v[80:81], v[8:9], off offset:1024
	v_pk_mul_f32 v[8:9], v[100:101], v[170:171]
	v_pk_mul_f32 v[30:31], v[68:69], v[172:173]
	v_pk_add_f32 v[32:33], v[188:189], 1.0 op_sel_hi:[1,0]
	v_pk_add_f32 v[34:35], v[186:187], 1.0 op_sel_hi:[1,0]
	v_pk_fma_f32 v[30:31], v[30:31], v[32:33], v[212:213]
	v_pk_fma_f32 v[8:9], v[8:9], v[34:35], v[210:211]
	v_cvt_pk_bf16_f32 v8, v8, v9
	v_cvt_pk_bf16_f32 v9, v30, v31
	global_store_dwordx2 v[80:81], v[8:9], off offset:1536
	v_pk_mul_f32 v[8:9], v[158:159], v[70:71]
	v_pk_mul_f32 v[30:31], v[160:161], v[66:67]
	v_pk_add_f32 v[32:33], v[176:177], 1.0 op_sel_hi:[1,0]
	v_pk_add_f32 v[34:35], v[174:175], 1.0 op_sel_hi:[1,0]
	v_pk_fma_f32 v[30:31], v[32:33], v[30:31], v[192:193]
	v_pk_fma_f32 v[8:9], v[34:35], v[8:9], v[190:191]
	v_cvt_pk_bf16_f32 v8, v8, v9
	v_cvt_pk_bf16_f32 v9, v30, v31
	global_store_dwordx2 v[78:79], v[8:9], off
	v_pk_mul_f32 v[8:9], v[162:163], v[96:97]
	v_pk_mul_f32 v[30:31], v[164:165], v[72:73]
	v_pk_add_f32 v[32:33], v[180:181], 1.0 op_sel_hi:[1,0]
	v_pk_add_f32 v[34:35], v[178:179], 1.0 op_sel_hi:[1,0]
	v_pk_fma_f32 v[30:31], v[32:33], v[30:31], v[196:197]
	v_pk_fma_f32 v[8:9], v[34:35], v[8:9], v[194:195]
	v_cvt_pk_bf16_f32 v8, v8, v9
	v_cvt_pk_bf16_f32 v9, v30, v31
	global_store_dwordx2 v[78:79], v[8:9], off offset:512
	ds_bpermute_b32 v7, v87, v103
	s_waitcnt lgkmcnt(0)
	v_add_f32_e32 v7, v103, v7
	v_pk_mul_f32 v[8:9], v[28:29], v[6:7] op_sel_hi:[1,0]
	v_pk_mul_f32 v[26:27], v[26:27], v[6:7] op_sel_hi:[1,0]
	v_pk_mul_f32 v[8:9], v[168:169], v[8:9]
	v_pk_mul_f32 v[26:27], v[166:167], v[26:27]
	v_pk_add_f32 v[28:29], v[184:185], 1.0 op_sel_hi:[1,0]
	v_pk_add_f32 v[30:31], v[182:183], 1.0 op_sel_hi:[1,0]
	v_pk_fma_f32 v[8:9], v[8:9], v[28:29], v[208:209]
	v_pk_fma_f32 v[26:27], v[26:27], v[30:31], v[206:207]
	v_cvt_pk_bf16_f32 v9, v8, v9
	v_cvt_pk_bf16_f32 v8, v26, v27
	global_store_dwordx2 v[78:79], v[8:9], off offset:1024
	ds_bpermute_b32 v8, v88, v7
	s_waitcnt lgkmcnt(0)
	v_add_f32_e32 v7, v7, v8
	ds_bpermute_b32 v8, v89, v7
	s_waitcnt lgkmcnt(0)
	v_add_f32_e32 v7, v7, v8
	v_fmamk_f32 v7, v7, 0x3a800000, v90
	v_cmp_gt_f32_e32 vcc, s3, v7
	v_mul_f32_e32 v8, 0x4f800000, v7
	s_nop 0
	v_cndmask_b32_e32 v38, v7, v8, vcc
	v_pk_mul_f32 v[8:9], v[24:25], v[6:7] op_sel_hi:[1,0]
	v_pk_mul_f32 v[6:7], v[22:23], v[6:7] op_sel_hi:[1,0]
	v_sqrt_f32_e32 v39, v38
	v_cmp_class_f32_e64 s[0:1], v38, v91
	v_pk_mul_f32 v[6:7], v[6:7], v[170:171]
	v_pk_mul_f32 v[8:9], v[8:9], v[172:173]
	v_pk_add_f32 v[22:23], v[188:189], 1.0 op_sel_hi:[1,0]
	v_pk_add_f32 v[24:25], v[186:187], 1.0 op_sel_hi:[1,0]
	v_pk_fma_f32 v[8:9], v[8:9], v[22:23], v[212:213]
	v_pk_fma_f32 v[6:7], v[6:7], v[24:25], v[210:211]
	v_cvt_pk_bf16_f32 v6, v6, v7
	v_cvt_pk_bf16_f32 v7, v8, v9
	global_store_dwordx2 v[78:79], v[6:7], off offset:1536
	v_add_u32_e32 v6, -1, v39
	v_add_u32_e32 v7, 1, v39
	v_fma_f32 v8, -v6, v39, v38
	v_fma_f32 v9, -v7, v39, v38
	v_cmp_ge_f32_e64 s[4:5], 0, v8
	v_cmp_lt_f32_e64 s[6:7], 0, v9
	s_nop 0
	v_cndmask_b32_e64 v6, v39, v6, s[4:5]
	v_cndmask_b32_e64 v6, v6, v7, s[6:7]
	v_mul_f32_e32 v7, 0x37800000, v6
	v_cndmask_b32_e32 v6, v6, v7, vcc
	v_cndmask_b32_e64 v6, v6, v38, s[0:1]
	v_div_scale_f32 v7, s[0:1], v6, v6, 1.0
	v_rcp_f32_e32 v9, v7
	v_div_scale_f32 v8, vcc, 1.0, v6, 1.0
	s_add_i32 s0, s38, 0x2000
	v_fma_f32 v34, -v7, v9, 1.0
	v_fmac_f32_e32 v9, v34, v9
	v_mul_f32_e32 v34, v8, v9
	v_fma_f32 v35, -v7, v34, v8
	v_fmac_f32_e32 v34, v35, v9
	v_fma_f32 v7, -v7, v34, v8
	v_div_fmas_f32 v7, v7, v9, v34
	v_div_fixup_f32 v6, v7, v6, 1.0
	v_pk_mul_f32 v[8:9], v[20:21], v[6:7] op_sel_hi:[1,0]
	v_pk_mul_f32 v[18:19], v[18:19], v[6:7] op_sel_hi:[1,0]
	s_cmpk_lt_i32 s38, 0x2000
	s_mov_b32 s38, s0
	v_pk_mul_f32 v[18:19], v[158:159], v[18:19]
	v_pk_mul_f32 v[8:9], v[160:161], v[8:9]
	v_pk_add_f32 v[20:21], v[176:177], 1.0 op_sel_hi:[1,0]
	v_pk_add_f32 v[22:23], v[174:175], 1.0 op_sel_hi:[1,0]
	v_pk_fma_f32 v[8:9], v[20:21], v[8:9], v[192:193]
	v_pk_fma_f32 v[18:19], v[22:23], v[18:19], v[190:191]
	v_bfe_u32 v21, v8, 16, 1
	v_bfe_u32 v7, v18, 16, 1
	v_bfe_u32 v20, v19, 16, 1
	v_bfe_u32 v22, v9, 16, 1
	v_add3_u32 v7, v18, v7, s26
	v_add3_u32 v8, v8, v21, s26
	v_add3_u32 v18, v19, v20, s26
	v_add3_u32 v9, v9, v22, s26
	v_lshrrev_b32_e32 v7, 16, v7
	v_lshrrev_b32_e32 v19, 16, v8
	v_and_or_b32 v8, v18, s27, v7
	v_and_or_b32 v9, v9, s27, v19
	global_store_dwordx2 v[76:77], v[8:9], off
	v_pk_mul_f32 v[8:9], v[16:17], v[6:7] op_sel_hi:[1,0]
	v_pk_mul_f32 v[14:15], v[14:15], v[6:7] op_sel_hi:[1,0]
	v_pk_mul_f32 v[8:9], v[164:165], v[8:9]
	v_pk_mul_f32 v[14:15], v[162:163], v[14:15]
	v_pk_add_f32 v[16:17], v[180:181], 1.0 op_sel_hi:[1,0]
	v_pk_add_f32 v[18:19], v[178:179], 1.0 op_sel_hi:[1,0]
	v_pk_fma_f32 v[8:9], v[16:17], v[8:9], v[196:197]
	v_pk_fma_f32 v[14:15], v[18:19], v[14:15], v[194:195]
	v_bfe_u32 v17, v8, 16, 1
	v_bfe_u32 v7, v14, 16, 1
	v_bfe_u32 v16, v15, 16, 1
	v_bfe_u32 v18, v9, 16, 1
	v_add3_u32 v7, v14, v7, s26
	v_add3_u32 v8, v8, v17, s26
	v_add3_u32 v14, v15, v16, s26
	v_add3_u32 v9, v9, v18, s26
	v_lshrrev_b32_e32 v7, 16, v7
	v_lshrrev_b32_e32 v15, 16, v8
	v_and_or_b32 v8, v14, s27, v7
	v_and_or_b32 v9, v9, s27, v15
	global_store_dwordx2 v[76:77], v[8:9], off offset:512
	v_pk_mul_f32 v[8:9], v[12:13], v[6:7] op_sel_hi:[1,0]
	v_pk_mul_f32 v[10:11], v[10:11], v[6:7] op_sel_hi:[1,0]
	v_pk_mul_f32 v[8:9], v[168:169], v[8:9]
	v_pk_mul_f32 v[10:11], v[166:167], v[10:11]
	v_pk_add_f32 v[12:13], v[184:185], 1.0 op_sel_hi:[1,0]
	v_pk_add_f32 v[14:15], v[182:183], 1.0 op_sel_hi:[1,0]
	v_pk_fma_f32 v[8:9], v[8:9], v[12:13], v[208:209]
	v_pk_fma_f32 v[10:11], v[10:11], v[14:15], v[206:207]
	v_bfe_u32 v13, v8, 16, 1
	v_bfe_u32 v7, v10, 16, 1
	v_bfe_u32 v12, v11, 16, 1
	v_bfe_u32 v14, v9, 16, 1
	v_add3_u32 v7, v10, v7, s26
	v_add3_u32 v8, v8, v13, s26
	v_add3_u32 v10, v11, v12, s26
	v_add3_u32 v9, v9, v14, s26
	v_lshrrev_b32_e32 v7, 16, v7
	v_lshrrev_b32_e32 v11, 16, v8
	v_and_or_b32 v8, v10, s27, v7
	v_and_or_b32 v9, v9, s27, v11
	global_store_dwordx2 v[76:77], v[8:9], off offset:1024
	s_nop 0
	v_pk_mul_f32 v[4:5], v[4:5], v[6:7] op_sel_hi:[1,0]
	v_pk_mul_f32 v[2:3], v[2:3], v[6:7] op_sel_hi:[1,0]
	v_pk_mul_f32 v[4:5], v[4:5], v[172:173]
	v_pk_mul_f32 v[2:3], v[2:3], v[170:171]
	v_pk_add_f32 v[6:7], v[188:189], 1.0 op_sel_hi:[1,0]
	v_pk_add_f32 v[8:9], v[186:187], 1.0 op_sel_hi:[1,0]
	v_pk_fma_f32 v[4:5], v[4:5], v[6:7], v[212:213]
	v_pk_fma_f32 v[2:3], v[2:3], v[8:9], v[210:211]
	v_cvt_pk_bf16_f32 v2, v2, v3
	v_cvt_pk_bf16_f32 v3, v4, v5
	global_store_dwordx2 v[76:77], v[2:3], off offset:1536
	s_cbranch_scc1 .LBB0_138
	v_readlane_b32 s16, v251, 9
	v_readlane_b32 s17, v251, 10
	v_readlane_b32 s18, v251, 11
	v_readlane_b32 s19, v251, 12
	v_readlane_b32 s20, v251, 13
	v_readlane_b32 s21, v251, 14
	v_readlane_b32 s22, v251, 15
	v_readlane_b32 s23, v251, 16
	v_readlane_b32 s24, v251, 17
	v_readlane_b32 s25, v251, 18
	v_readlane_b32 s26, v251, 19
	v_readlane_b32 s27, v251, 20
	v_readlane_b32 s28, v251, 21
	v_readlane_b32 s29, v251, 22
	v_readlane_b32 s30, v251, 23
	v_readlane_b32 s31, v251, 24
	v_readlane_b32 s16, v251, 25
	v_readlane_b32 s17, v251, 26
	v_readlane_b32 s18, v251, 27
	v_readlane_b32 s19, v251, 28
	v_readlane_b32 s20, v251, 29
	v_readlane_b32 s21, v251, 30
	v_readlane_b32 s22, v251, 31
	v_readlane_b32 s23, v251, 32
	v_readlane_b32 s24, v251, 33
	v_readlane_b32 s25, v251, 34
	v_readlane_b32 s26, v251, 35
	v_readlane_b32 s27, v251, 36
	v_readlane_b32 s28, v251, 37
	v_readlane_b32 s29, v251, 38
	v_readlane_b32 s30, v251, 39
	v_readlane_b32 s31, v251, 40
